# c7: attn_b relative-bias lookups issued in batches (masked lanes read an extra table slot holding -1024 so exp2 gives exactly 0)
# speedup vs baseline: 1.0251x; 1.0036x over previous
; __device__ void attn_b_item(const Params& p, int item, int l, unsigned char* smem) {
;     ...
;     if (tid < 129) {
;         const int rel = tid - 64, n = (rel < 0 ? -rel : rel) * dil;
;         int bk;
;         if (n < 8) bk = n; else { bk = 8 + (n >= 15) + (n >= 27) + (n >= 50) + (n >= 91) + (n >= 166) + (n >= 305) + (n >= 559); }
;         if (rel > 0) bk += 16;
;         lut[tid] = p.rel_bias[bk * 12 + g * 4 + j] * LOG2E;
;     }
; #pragma unroll
;     for (int kt = 0; kt < 6; ++kt) { unsigned char* tb = smem + kt * ATB_TILE;
;         *(u32x4*)(tb + srow * 144 + sch * 16) = rk[kt]; *(u32x4*)(tb + 9216 + (sch >> 2) * 4096 + srow * 64 + (sch & 3) * 16) = rv[kt]; }
;     const int qpos = p0r + w * 32 + r32;
;     bf16x8 qr[4];
; #pragma unroll
;     for (int ds = 0; ds < 4; ++ds) qr[ds] = *(const bf16x8*)(QB + (size_t)qpos * 256 + ds * 16 + hi * 8);
;     const float nshift = -((const float*)(p.ws + WS_BND))[2 + l];
;     f32x16 o0, o1;
; #pragma unroll
;     for (int i = 0; i < 16; ++i) { o0[i] = 0.f; o1[i] = 0.f; }
;     f32x4 la4 = (f32x4){0.f, 0.f, 0.f, 0.f};
;     __syncthreads();
.LBB0_786:
	s_or_b64 exec, exec, s[36:37]
	v_mov_b32_e32 v148, 0xc4800000
	v_mov_b32_e32 v149, 0x19e04
	ds_write_b32 v149, v148
	s_lshr_b32 s22, 0x2000, s16
	s_sub_i32 s16, 13, s16
	s_lshl_b64 s[36:37], s[42:43], 21
	s_ashr_i32 s58, s17, 1
	v_mul_lo_u32 v52, v49, s3
	s_lshr_b32 s59, s9, s16
	v_readlane_b32 s16, v255, 4
	s_lshl_b32 s18, s54, 6
	s_and_b32 s19, s52, 0x1f00
	s_lshl_b64 s[20:21], s[36:37], 1
	v_lshlrev_b32_e32 v50, 10, v50
	s_andn2_b32 s58, s58, 31
	v_add3_u32 v57, s16, v52, v80
	v_readlane_b32 s16, v255, 6
	v_and_b32_e32 v50, 0x1000, v50
	v_add3_u32 v56, 0, v52, v80
	v_add3_u32 v52, s16, v52, v80
	s_add_u32 s16, s48, s20
	v_readlane_b32 s20, v255, 5
	s_waitcnt vmcnt(11)
	ds_write_b128 v56, v[36:39]
	v_and_b32_e32 v137, 31, v48
	v_add_u32_e32 v37, s20, v50
	v_readlane_b32 s20, v255, 7
	v_lshlrev_b32_e32 v53, 4, v48
	v_lshlrev_b32_e32 v49, 6, v49
	v_add_u32_e32 v38, s20, v50
	s_addc_u32 s20, s49, s21
	s_lshl_b32 s18, s18, 1
	s_add_u32 s44, s16, s18
	s_addc_u32 s45, s20, 0
	s_add_i32 s55, s58, s9
	v_and_b32_e32 v55, 48, v53
	v_add_u32_e32 v36, 0, v50
	v_or_b32_e32 v130, s55, v137
	v_add3_u32 v36, v36, v49, v55
	v_ashrrev_i32_e32 v131, 31, v130
	global_load_dword v138, v81, s[40:41]
	v_bfe_u32 v51, v48, 5, 1
	s_waitcnt vmcnt(11)
	ds_write_b128 v36, v[20:23] offset:9216
	s_waitcnt vmcnt(10)
	ds_write_b128 v56, v[32:35] offset:17408
	v_lshlrev_b64 v[20:21], 9, v[130:131]
	v_lshlrev_b32_e32 v80, 4, v51
	v_lshl_add_u64 v[20:21], s[44:45], 0, v[20:21]
	v_lshl_add_u64 v[20:21], v[20:21], 0, v[80:81]
	global_load_dwordx4 v[82:85], v[20:21], off
	global_load_dwordx4 v[86:89], v[20:21], off offset:32
	global_load_dwordx4 v[90:93], v[20:21], off offset:64
	global_load_dwordx4 v[94:97], v[20:21], off offset:96
	s_ashr_i32 s61, s17, 7
	v_lshlrev_b32_e32 v136, 2, v51
	s_lshl_b32 s9, s61, 6
	v_add3_u32 v37, v37, v49, v55
	v_add3_u32 v38, v38, v49, v55
	s_waitcnt vmcnt(13)
	ds_write_b128 v36, v[8:11] offset:26624
	s_waitcnt vmcnt(12)
	ds_write_b128 v56, v[0:3] offset:34816
	s_waitcnt vmcnt(11)
	ds_write_b128 v36, v[4:7] offset:44032
	s_waitcnt vmcnt(10)
	ds_write_b128 v56, v[12:15] offset:52224
	s_waitcnt vmcnt(9)
	ds_write_b128 v36, v[16:19] offset:61440
	s_waitcnt vmcnt(8)
	ds_write_b128 v57, v[24:27]
	s_waitcnt vmcnt(7)
	ds_write_b128 v37, v[28:31]
	s_waitcnt vmcnt(6)
	ds_write_b128 v52, v[40:43]
	s_waitcnt vmcnt(5)
	ds_write_b128 v38, v[44:47]
	v_or_b32_e32 v0, s9, v136
	v_sub_u32_e32 v0, v0, v137
	v_and_b32_e32 v139, 63, v48
	v_lshlrev_b32_e32 v54, 1, v48
	v_lshlrev_b32_e32 v48, 3, v48
	s_add_i32 s19, s19, s9
	v_subrev_u32_e32 v141, s58, v0
	v_and_b32_e32 v0, 0xc0, v53
	s_movk_i32 s9, 0x100
	v_and_b32_e32 v54, 32, v54
	v_and_b32_e32 v59, 24, v48
	v_and_or_b32 v0, v48, s9, v0
	v_mul_u32_u24_e32 v58, 0x90, v137
	s_mul_i32 s59, s59, s22
	v_or3_b32 v0, v0, v54, v59
	v_mov_b32_e32 v132, 0
	s_add_i32 s60, s59, s22
	v_or_b32_e32 v140, s19, v136
	s_mulk_i32 s61, 0x4400
	v_add_u32_e32 v142, 0, v0
	v_add3_u32 v80, v58, v80, 0
	s_mov_b32 s62, 0
	v_mov_b32_e32 v133, v132
	v_mov_b32_e32 v134, v132
	v_mov_b32_e32 v135, v132
	v_mov_b32_e32 v0, v132
	v_mov_b32_e32 v1, v132
	v_mov_b32_e32 v2, v132
	v_mov_b32_e32 v3, v132
	v_mov_b32_e32 v4, v132
	v_mov_b32_e32 v5, v132
	v_mov_b32_e32 v6, v132
	v_mov_b32_e32 v7, v132
	v_mov_b32_e32 v8, v132
	v_mov_b32_e32 v9, v132
	v_mov_b32_e32 v10, v132
	v_mov_b32_e32 v11, v132
	v_mov_b32_e32 v12, v132
	v_mov_b32_e32 v13, v132
	v_mov_b32_e32 v14, v132
	v_mov_b32_e32 v15, v132
	v_mov_b32_e32 v16, v132
	v_mov_b32_e32 v17, v132
	v_mov_b32_e32 v18, v132
	v_mov_b32_e32 v19, v132
	v_mov_b32_e32 v20, v132
	v_mov_b32_e32 v21, v132
	v_mov_b32_e32 v22, v132
	v_mov_b32_e32 v23, v132
	v_mov_b32_e32 v24, v132
	v_mov_b32_e32 v25, v132
	v_mov_b32_e32 v26, v132
	v_mov_b32_e32 v27, v132
	v_mov_b32_e32 v28, v132
	v_mov_b32_e32 v29, v132
	v_mov_b32_e32 v30, v132
	v_mov_b32_e32 v31, v132
	s_waitcnt lgkmcnt(0)
	s_barrier
	s_waitcnt vmcnt(4)
	v_xor_b32_e32 v32, 0x80000000, v138
	v_mov_b32_e32 v33, v32
	v_mov_b32_e32 v34, v32
	v_mov_b32_e32 v35, v32
	v_mov_b32_e32 v36, v32
	v_mov_b32_e32 v37, v32
	v_mov_b32_e32 v38, v32
	v_mov_b32_e32 v39, v32
	v_mov_b32_e32 v40, v32
	v_mov_b32_e32 v41, v32
	v_mov_b32_e32 v42, v32
	v_mov_b32_e32 v43, v32
	v_mov_b32_e32 v44, v32
	v_mov_b32_e32 v45, v32
	v_mov_b32_e32 v46, v32
	v_mov_b32_e32 v47, v32
; __device__ __forceinline__ int crow(int r, int hi) { return (r & 3) + 8 * (r >> 2) + 4 * hi; }
; __device__ void attn_b_item(const Params& p, int item, int l, unsigned char* smem) {
;     ...
; #pragma unroll 1
;     for (int t3 = 0; t3 < 3; ++t3) {
;         const int kt = (w >> 1) + t3, kbase = p0r - 64 + 64 * kt;
;         const bf16_t* Ks = (const bf16_t*)(smem + kt * ATB_TILE); const unsigned char* Vs = smem + kt * ATB_TILE + 9216;
;         f32x16 p0, p1;
; #pragma unroll
;         for (int i = 0; i < 16; ++i) { p0[i] = nshift; p1[i] = nshift; }
;         at_qk(p0, p1, Ks, qr, r32, hi);
;         bf16x8 vf0[4], vf1[4];
;         at_ldv(vf0, vf1, Vs, lane); __builtin_amdgcn_sched_barrier(0);
; #pragma unroll
;         for (int i = 0; i < 16; ++i) {
;             const int kv0 = kbase + crow(i, hi), kv1 = kv0 + 32;
;             const int rel0 = kv0 - qpos, rel1 = kv1 - qpos;
;             const bool ok0 = rel0 >= -64 && rel0 <= 64 && kv0 >= seq_lo && kv0 < seq_hi;
;             const bool ok1 = rel1 >= -64 && rel1 <= 64 && kv1 >= seq_lo && kv1 < seq_hi;
;             const float e0 = __builtin_amdgcn_exp2f(p0[i] + lut[ok0 ? rel0 + 64 : 64]);
;             const float e1 = __builtin_amdgcn_exp2f(p1[i] + lut[ok1 ? rel1 + 64 : 64]);
;             p0[i] = ok0 ? e0 : 0.f; p1[i] = ok1 ? e1 : 0.f;
;         }
.LBB0_787:
	v_add_u32_e32 v52, s61, v80
	ds_read_b128 v[48:51], v52
	ds_read_b128 v[98:101], v52 offset:32
	ds_read_b128 v[102:105], v52 offset:4608
	ds_read_b128 v[106:109], v52 offset:4640
	ds_read_b128 v[110:113], v52 offset:64
	ds_read_b128 v[114:117], v52 offset:96
	ds_read_b128 v[118:121], v52 offset:4672
	ds_read_b128 v[122:125], v52 offset:4704
	s_setprio 1
	s_waitcnt vmcnt(3) lgkmcnt(7)
	v_mfma_f32_32x32x16_bf16 v[64:79], v[48:51], v[82:85], v[32:47]
	s_waitcnt lgkmcnt(5)
	v_mfma_f32_32x32x16_bf16 v[48:63], v[102:105], v[82:85], v[32:47]
	s_waitcnt vmcnt(2)
	v_mfma_f32_32x32x16_bf16 v[64:79], v[98:101], v[86:89], v[64:79]
	s_waitcnt lgkmcnt(4)
	v_mfma_f32_32x32x16_bf16 v[48:63], v[106:109], v[86:89], v[48:63]
	s_waitcnt vmcnt(1) lgkmcnt(3)
	v_mfma_f32_32x32x16_bf16 v[64:79], v[110:113], v[90:93], v[64:79]
	s_waitcnt lgkmcnt(1)
	v_mfma_f32_32x32x16_bf16 v[48:63], v[118:121], v[90:93], v[48:63]
	s_waitcnt vmcnt(0)
	v_mfma_f32_32x32x16_bf16 v[64:79], v[114:117], v[94:97], v[64:79]
	s_waitcnt lgkmcnt(0)
	v_mfma_f32_32x32x16_bf16 v[48:63], v[122:125], v[94:97], v[48:63]
	s_setprio 0
	v_add_u32_e32 v104, s61, v142
	ds_read_b64_tr_b16 v[122:123], v104 offset:9216
	ds_read_b64_tr_b16 v[124:125], v104 offset:9728
	ds_read_b64_tr_b16 v[110:111], v104 offset:10240
	ds_read_b64_tr_b16 v[112:113], v104 offset:10752
	ds_read_b64_tr_b16 v[126:127], v104 offset:13312
	ds_read_b64_tr_b16 v[128:129], v104 offset:13824
	ds_read_b64_tr_b16 v[118:119], v104 offset:14336
	ds_read_b64_tr_b16 v[120:121], v104 offset:14848
	ds_read_b64_tr_b16 v[106:107], v104 offset:11264
	ds_read_b64_tr_b16 v[108:109], v104 offset:11776
	ds_read_b64_tr_b16 v[98:99], v104 offset:12288
	ds_read_b64_tr_b16 v[100:101], v104 offset:12800
	ds_read_b64_tr_b16 v[114:115], v104 offset:15360
	ds_read_b64_tr_b16 v[116:117], v104 offset:15872
	ds_read_b64_tr_b16 v[102:103], v104 offset:16384
	ds_read_b64_tr_b16 v[104:105], v104 offset:16896
	s_add_i32 s9, 0, 0x19c00
	v_add_u32_e32 v144, s62, v140
	v_add_u32_e32 v143, s62, v141
	s_sub_i32 s99, s60, s59
	v_mov_b32_e32 v184, 0x81
	v_subrev_u32_e32 v180, s59, v144
	v_subrev_u32_e32 v180, 64, v180
	s_waitcnt lgkmcnt(0)
	v_add_u32_e32 v148, 0, v143
	v_add_u32_e32 v182, 0, v180
	v_add_u32_e32 v149, 32, v143
	v_add_u32_e32 v183, 32, v180
	v_cmp_gt_u32_e32 vcc, s4, v148
	v_cmp_gt_u32_e64 s[36:37], s99, v182
	v_cmp_gt_u32_e64 s[38:39], s4, v149
	v_cmp_gt_u32_e64 s[16:17], s99, v183
	s_and_b64 vcc, vcc, s[36:37]
	s_and_b64 s[38:39], s[38:39], s[16:17]
	v_cndmask_b32_e32 v148, v184, v148, vcc
	v_cndmask_b32_e64 v149, v184, v149, s[38:39]
	v_lshl_add_u32 v148, v148, 2, s9
	v_lshl_add_u32 v149, v149, 2, s9
	ds_read_b32 v148, v148
	ds_read_b32 v149, v149
	v_add_u32_e32 v150, 1, v143
	v_add_u32_e32 v182, 1, v180
	v_add_u32_e32 v151, 33, v143
	v_add_u32_e32 v183, 33, v180
	v_cmp_gt_u32_e32 vcc, s4, v150
	v_cmp_gt_u32_e64 s[36:37], s99, v182
	v_cmp_gt_u32_e64 s[38:39], s4, v151
	v_cmp_gt_u32_e64 s[16:17], s99, v183
	s_and_b64 vcc, vcc, s[36:37]
	s_and_b64 s[38:39], s[38:39], s[16:17]
	v_cndmask_b32_e32 v150, v184, v150, vcc
	v_cndmask_b32_e64 v151, v184, v151, s[38:39]
	v_lshl_add_u32 v150, v150, 2, s9
	v_lshl_add_u32 v151, v151, 2, s9
	ds_read_b32 v150, v150
	ds_read_b32 v151, v151
	v_add_u32_e32 v152, 2, v143
	v_add_u32_e32 v182, 2, v180
	v_add_u32_e32 v153, 34, v143
	v_add_u32_e32 v183, 34, v180
	v_cmp_gt_u32_e32 vcc, s4, v152
	v_cmp_gt_u32_e64 s[36:37], s99, v182
	v_cmp_gt_u32_e64 s[38:39], s4, v153
	v_cmp_gt_u32_e64 s[16:17], s99, v183
	s_and_b64 vcc, vcc, s[36:37]
	s_and_b64 s[38:39], s[38:39], s[16:17]
	v_cndmask_b32_e32 v152, v184, v152, vcc
	v_cndmask_b32_e64 v153, v184, v153, s[38:39]
	v_lshl_add_u32 v152, v152, 2, s9
	v_lshl_add_u32 v153, v153, 2, s9
	ds_read_b32 v152, v152
	ds_read_b32 v153, v153
	v_add_u32_e32 v154, 3, v143
	v_add_u32_e32 v182, 3, v180
	v_add_u32_e32 v155, 35, v143
	v_add_u32_e32 v183, 35, v180
	v_cmp_gt_u32_e32 vcc, s4, v154
	v_cmp_gt_u32_e64 s[36:37], s99, v182
	v_cmp_gt_u32_e64 s[38:39], s4, v155
	v_cmp_gt_u32_e64 s[16:17], s99, v183
	s_and_b64 vcc, vcc, s[36:37]
	s_and_b64 s[38:39], s[38:39], s[16:17]
	v_cndmask_b32_e32 v154, v184, v154, vcc
	v_cndmask_b32_e64 v155, v184, v155, s[38:39]
	v_lshl_add_u32 v154, v154, 2, s9
	v_lshl_add_u32 v155, v155, 2, s9
	ds_read_b32 v154, v154
	ds_read_b32 v155, v155
	s_waitcnt lgkmcnt(6)
	v_add_f32_e32 v64, v64, v148
	v_add_f32_e32 v48, v48, v149
	v_exp_f32_e32 v181, v64
	v_exp_f32_e32 v64, v48
	v_mov_b32_e32 v48, v181
	s_waitcnt lgkmcnt(4)
	v_add_f32_e32 v65, v65, v150
	v_add_f32_e32 v49, v49, v151
	v_exp_f32_e32 v181, v65
	v_exp_f32_e32 v65, v49
	v_mov_b32_e32 v49, v181
	s_waitcnt lgkmcnt(2)
	v_add_f32_e32 v66, v66, v152
	v_add_f32_e32 v50, v50, v153
	v_exp_f32_e32 v181, v66
	v_exp_f32_e32 v66, v50
	v_mov_b32_e32 v50, v181
	s_waitcnt lgkmcnt(0)
; __device__ __forceinline__ int crow(int r, int hi) { return (r & 3) + 8 * (r >> 2) + 4 * hi; }
; __device__ void attn_b_item(const Params& p, int item, int l, unsigned char* smem) {
;     ...
;         for (int i = 0; i < 16; ++i) {
;             const int kv0 = kbase + crow(i, hi), kv1 = kv0 + 32;
;             const int rel0 = kv0 - qpos, rel1 = kv1 - qpos;
;             const bool ok0 = rel0 >= -64 && rel0 <= 64 && kv0 >= seq_lo && kv0 < seq_hi;
;             const bool ok1 = rel1 >= -64 && rel1 <= 64 && kv1 >= seq_lo && kv1 < seq_hi;
;             const float e0 = __builtin_amdgcn_exp2f(p0[i] + lut[ok0 ? rel0 + 64 : 64]);
;             const float e1 = __builtin_amdgcn_exp2f(p1[i] + lut[ok1 ? rel1 + 64 : 64]);
;             p0[i] = ok0 ? e0 : 0.f; p1[i] = ok1 ? e1 : 0.f;
;         }
	v_add_f32_e32 v67, v67, v154
	v_add_f32_e32 v51, v51, v155
	v_exp_f32_e32 v181, v67
	v_exp_f32_e32 v67, v51
	v_mov_b32_e32 v51, v181
	v_add_u32_e32 v156, 8, v143
	v_add_u32_e32 v182, 8, v180
	v_add_u32_e32 v157, 40, v143
	v_add_u32_e32 v183, 40, v180
	v_cmp_gt_u32_e32 vcc, s4, v156
	v_cmp_gt_u32_e64 s[36:37], s99, v182
	v_cmp_gt_u32_e64 s[38:39], s4, v157
	v_cmp_gt_u32_e64 s[16:17], s99, v183
	s_and_b64 vcc, vcc, s[36:37]
	s_and_b64 s[38:39], s[38:39], s[16:17]
	v_cndmask_b32_e32 v156, v184, v156, vcc
	v_cndmask_b32_e64 v157, v184, v157, s[38:39]
	v_lshl_add_u32 v156, v156, 2, s9
	v_lshl_add_u32 v157, v157, 2, s9
	ds_read_b32 v156, v156
	ds_read_b32 v157, v157
	v_add_u32_e32 v158, 9, v143
	v_add_u32_e32 v182, 9, v180
	v_add_u32_e32 v159, 41, v143
	v_add_u32_e32 v183, 41, v180
	v_cmp_gt_u32_e32 vcc, s4, v158
	v_cmp_gt_u32_e64 s[36:37], s99, v182
	v_cmp_gt_u32_e64 s[38:39], s4, v159
	v_cmp_gt_u32_e64 s[16:17], s99, v183
	s_and_b64 vcc, vcc, s[36:37]
	s_and_b64 s[38:39], s[38:39], s[16:17]
	v_cndmask_b32_e32 v158, v184, v158, vcc
	v_cndmask_b32_e64 v159, v184, v159, s[38:39]
	v_lshl_add_u32 v158, v158, 2, s9
	v_lshl_add_u32 v159, v159, 2, s9
	ds_read_b32 v158, v158
	ds_read_b32 v159, v159
	v_add_u32_e32 v160, 10, v143
	v_add_u32_e32 v182, 10, v180
	v_add_u32_e32 v161, 42, v143
	v_add_u32_e32 v183, 42, v180
	v_cmp_gt_u32_e32 vcc, s4, v160
	v_cmp_gt_u32_e64 s[36:37], s99, v182
	v_cmp_gt_u32_e64 s[38:39], s4, v161
	v_cmp_gt_u32_e64 s[16:17], s99, v183
	s_and_b64 vcc, vcc, s[36:37]
	s_and_b64 s[38:39], s[38:39], s[16:17]
	v_cndmask_b32_e32 v160, v184, v160, vcc
	v_cndmask_b32_e64 v161, v184, v161, s[38:39]
	v_lshl_add_u32 v160, v160, 2, s9
	v_lshl_add_u32 v161, v161, 2, s9
	ds_read_b32 v160, v160
	ds_read_b32 v161, v161
	v_add_u32_e32 v162, 11, v143
	v_add_u32_e32 v182, 11, v180
	v_add_u32_e32 v163, 43, v143
	v_add_u32_e32 v183, 43, v180
	v_cmp_gt_u32_e32 vcc, s4, v162
	v_cmp_gt_u32_e64 s[36:37], s99, v182
	v_cmp_gt_u32_e64 s[38:39], s4, v163
	v_cmp_gt_u32_e64 s[16:17], s99, v183
	s_and_b64 vcc, vcc, s[36:37]
	s_and_b64 s[38:39], s[38:39], s[16:17]
	v_cndmask_b32_e32 v162, v184, v162, vcc
	v_cndmask_b32_e64 v163, v184, v163, s[38:39]
	v_lshl_add_u32 v162, v162, 2, s9
	v_lshl_add_u32 v163, v163, 2, s9
	ds_read_b32 v162, v162
	ds_read_b32 v163, v163
	s_waitcnt lgkmcnt(6)
	v_add_f32_e32 v68, v68, v156
	v_add_f32_e32 v52, v52, v157
	v_exp_f32_e32 v181, v68
	v_exp_f32_e32 v68, v52
	v_mov_b32_e32 v52, v181
	s_waitcnt lgkmcnt(4)
	v_add_f32_e32 v69, v69, v158
	v_add_f32_e32 v53, v53, v159
	v_exp_f32_e32 v181, v69
	v_exp_f32_e32 v69, v53
	v_mov_b32_e32 v53, v181
	s_waitcnt lgkmcnt(2)
	v_add_f32_e32 v70, v70, v160
	v_add_f32_e32 v54, v54, v161
	v_exp_f32_e32 v181, v70
	v_exp_f32_e32 v70, v54
	v_mov_b32_e32 v54, v181
	s_waitcnt lgkmcnt(0)
	v_add_f32_e32 v71, v71, v162
	v_add_f32_e32 v55, v55, v163
	v_exp_f32_e32 v181, v71
	v_exp_f32_e32 v71, v55
	v_mov_b32_e32 v55, v181
	v_add_u32_e32 v164, 16, v143
	v_add_u32_e32 v182, 16, v180
	v_add_u32_e32 v165, 48, v143
	v_add_u32_e32 v183, 48, v180
	v_cmp_gt_u32_e32 vcc, s4, v164
	v_cmp_gt_u32_e64 s[36:37], s99, v182
	v_cmp_gt_u32_e64 s[38:39], s4, v165
	v_cmp_gt_u32_e64 s[16:17], s99, v183
	s_and_b64 vcc, vcc, s[36:37]
	s_and_b64 s[38:39], s[38:39], s[16:17]
	v_cndmask_b32_e32 v164, v184, v164, vcc
	v_cndmask_b32_e64 v165, v184, v165, s[38:39]
	v_lshl_add_u32 v164, v164, 2, s9
	v_lshl_add_u32 v165, v165, 2, s9
	ds_read_b32 v164, v164
	ds_read_b32 v165, v165
	v_add_u32_e32 v166, 17, v143
	v_add_u32_e32 v182, 17, v180
	v_add_u32_e32 v167, 49, v143
	v_add_u32_e32 v183, 49, v180
	v_cmp_gt_u32_e32 vcc, s4, v166
	v_cmp_gt_u32_e64 s[36:37], s99, v182
	v_cmp_gt_u32_e64 s[38:39], s4, v167
	v_cmp_gt_u32_e64 s[16:17], s99, v183
	s_and_b64 vcc, vcc, s[36:37]
	s_and_b64 s[38:39], s[38:39], s[16:17]
	v_cndmask_b32_e32 v166, v184, v166, vcc
	v_cndmask_b32_e64 v167, v184, v167, s[38:39]
	v_lshl_add_u32 v166, v166, 2, s9
	v_lshl_add_u32 v167, v167, 2, s9
	ds_read_b32 v166, v166
	ds_read_b32 v167, v167
	v_add_u32_e32 v168, 18, v143
	v_add_u32_e32 v182, 18, v180
	v_add_u32_e32 v169, 50, v143
	v_add_u32_e32 v183, 50, v180
	v_cmp_gt_u32_e32 vcc, s4, v168
	v_cmp_gt_u32_e64 s[36:37], s99, v182
	v_cmp_gt_u32_e64 s[38:39], s4, v169
	v_cmp_gt_u32_e64 s[16:17], s99, v183
	s_and_b64 vcc, vcc, s[36:37]
	s_and_b64 s[38:39], s[38:39], s[16:17]
	v_cndmask_b32_e32 v168, v184, v168, vcc
	v_cndmask_b32_e64 v169, v184, v169, s[38:39]
	v_lshl_add_u32 v168, v168, 2, s9
	v_lshl_add_u32 v169, v169, 2, s9
	ds_read_b32 v168, v168
	ds_read_b32 v169, v169
	v_add_u32_e32 v170, 19, v143
	v_add_u32_e32 v182, 19, v180
	v_add_u32_e32 v171, 51, v143
	v_add_u32_e32 v183, 51, v180
	v_cmp_gt_u32_e32 vcc, s4, v170
	v_cmp_gt_u32_e64 s[36:37], s99, v182
	v_cmp_gt_u32_e64 s[38:39], s4, v171
	v_cmp_gt_u32_e64 s[16:17], s99, v183
	s_and_b64 vcc, vcc, s[36:37]
	s_and_b64 s[38:39], s[38:39], s[16:17]
	v_cndmask_b32_e32 v170, v184, v170, vcc
	v_cndmask_b32_e64 v171, v184, v171, s[38:39]
	v_lshl_add_u32 v170, v170, 2, s9
	v_lshl_add_u32 v171, v171, 2, s9
	ds_read_b32 v170, v170
	ds_read_b32 v171, v171
	s_waitcnt lgkmcnt(6)
	v_add_f32_e32 v72, v72, v164
	v_add_f32_e32 v56, v56, v165
	v_exp_f32_e32 v181, v72
	v_exp_f32_e32 v72, v56
	v_mov_b32_e32 v56, v181
	s_waitcnt lgkmcnt(4)
	v_add_f32_e32 v73, v73, v166
	v_add_f32_e32 v57, v57, v167
	v_exp_f32_e32 v181, v73
	v_exp_f32_e32 v73, v57
	v_mov_b32_e32 v57, v181
	s_waitcnt lgkmcnt(2)
	v_add_f32_e32 v74, v74, v168
	v_add_f32_e32 v58, v58, v169
	v_exp_f32_e32 v181, v74
	v_exp_f32_e32 v74, v58
	v_mov_b32_e32 v58, v181
	s_waitcnt lgkmcnt(0)
; __device__ __forceinline__ unsigned pk2(float lo, float hi) { f32x2 v = {lo, hi}; bf16x2_t b = __builtin_convertvector(v, bf16x2_t); return __builtin_bit_cast(unsigned, b); }
; __device__ __forceinline__ void at_pv2(f32x16& o0, f32x16& o1, const f32x16& p0, const f32x16& p1, const bf16x8 (&v0)[4], const bf16x8 (&v1)[4]) {
;     ...
;     for (int s = 0; s < 4; ++s) {
;         u32x4 pw;
;         if (s < 2) { pw.x = pk2(p0[8 * s + 0], p0[8 * s + 1]); pw.y = pk2(p0[8 * s + 2], p0[8 * s + 3]); pw.z = pk2(p0[8 * s + 4], p0[8 * s + 5]); pw.w = pk2(p0[8 * s + 6], p0[8 * s + 7]); }
;         else { const int q = s - 2; pw.x = pk2(p1[8 * q + 0], p1[8 * q + 1]); pw.y = pk2(p1[8 * q + 2], p1[8 * q + 3]); pw.z = pk2(p1[8 * q + 4], p1[8 * q + 5]); pw.w = pk2(p1[8 * q + 6], p1[8 * q + 7]); }
;         pa[s] = __builtin_bit_cast(bf16x8, pw);
;     }
;     __builtin_amdgcn_sched_barrier(0);
;     __builtin_amdgcn_s_setprio(1);
; #pragma unroll
;     for (int s = 0; s < 4; ++s) {
;         o0 = __builtin_amdgcn_mfma_f32_32x32x16_bf16(pa[s], v0[s], o0, 0, 0, 0);
;         o1 = __builtin_amdgcn_mfma_f32_32x32x16_bf16(pa[s], v1[s], o1, 0, 0, 0);
;     }
;     __builtin_amdgcn_s_setprio(0);
; __device__ void attn_b_item(const Params& p, int item, int l, unsigned char* smem) {
;     ...
;         for (int i = 0; i < 16; ++i) {
;             const int kv0 = kbase + crow(i, hi), kv1 = kv0 + 32;
;             const int rel0 = kv0 - qpos, rel1 = kv1 - qpos;
;             const bool ok0 = rel0 >= -64 && rel0 <= 64 && kv0 >= seq_lo && kv0 < seq_hi;
;             const bool ok1 = rel1 >= -64 && rel1 <= 64 && kv1 >= seq_lo && kv1 < seq_hi;
;             const float e0 = __builtin_amdgcn_exp2f(p0[i] + lut[ok0 ? rel0 + 64 : 64]);
;             const float e1 = __builtin_amdgcn_exp2f(p1[i] + lut[ok1 ? rel1 + 64 : 64]);
;             p0[i] = ok0 ? e0 : 0.f; p1[i] = ok1 ? e1 : 0.f;
;         }
; #pragma unroll
;         for (int i = 0; i < 4; ++i) { la4 += (f32x4){p0[4 * i], p0[4 * i + 1], p0[4 * i + 2], p0[4 * i + 3]}; la4 += (f32x4){p1[4 * i], p1[4 * i + 1], p1[4 * i + 2], p1[4 * i + 3]}; }
;         at_pv2(o0, o1, p0, p1, vf0, vf1);
;     }
;     float lacc = (la4.x + la4.y) + (la4.z + la4.w);
;     lacc += __shfl_xor(lacc, 32);
;     if (hi == 0) { lq[r32] = lacc; LSE[(size_t)qpos * 4] = (-nshift + log2f(lacc)) * LN2; }
	v_add_f32_e32 v75, v75, v170
	v_add_f32_e32 v59, v59, v171
	v_exp_f32_e32 v181, v75
	v_exp_f32_e32 v75, v59
	v_mov_b32_e32 v59, v181
	v_add_u32_e32 v172, 24, v143
	v_add_u32_e32 v182, 24, v180
	v_add_u32_e32 v173, 56, v143
	v_add_u32_e32 v183, 56, v180
	v_cmp_gt_u32_e32 vcc, s4, v172
	v_cmp_gt_u32_e64 s[36:37], s99, v182
	v_cmp_gt_u32_e64 s[38:39], s4, v173
	v_cmp_gt_u32_e64 s[16:17], s99, v183
	s_and_b64 vcc, vcc, s[36:37]
	s_and_b64 s[38:39], s[38:39], s[16:17]
	v_cndmask_b32_e32 v172, v184, v172, vcc
	v_cndmask_b32_e64 v173, v184, v173, s[38:39]
	v_lshl_add_u32 v172, v172, 2, s9
	v_lshl_add_u32 v173, v173, 2, s9
	ds_read_b32 v172, v172
	ds_read_b32 v173, v173
	v_add_u32_e32 v174, 25, v143
	v_add_u32_e32 v182, 25, v180
	v_add_u32_e32 v175, 57, v143
	v_add_u32_e32 v183, 57, v180
	v_cmp_gt_u32_e32 vcc, s4, v174
	v_cmp_gt_u32_e64 s[36:37], s99, v182
	v_cmp_gt_u32_e64 s[38:39], s4, v175
	v_cmp_gt_u32_e64 s[16:17], s99, v183
	s_and_b64 vcc, vcc, s[36:37]
	s_and_b64 s[38:39], s[38:39], s[16:17]
	v_cndmask_b32_e32 v174, v184, v174, vcc
	v_cndmask_b32_e64 v175, v184, v175, s[38:39]
	v_lshl_add_u32 v174, v174, 2, s9
	v_lshl_add_u32 v175, v175, 2, s9
	ds_read_b32 v174, v174
	ds_read_b32 v175, v175
	v_add_u32_e32 v176, 26, v143
	v_add_u32_e32 v182, 26, v180
	v_add_u32_e32 v177, 58, v143
	v_add_u32_e32 v183, 58, v180
	v_cmp_gt_u32_e32 vcc, s4, v176
	v_cmp_gt_u32_e64 s[36:37], s99, v182
	v_cmp_gt_u32_e64 s[38:39], s4, v177
	v_cmp_gt_u32_e64 s[16:17], s99, v183
	s_and_b64 vcc, vcc, s[36:37]
	s_and_b64 s[38:39], s[38:39], s[16:17]
	v_cndmask_b32_e32 v176, v184, v176, vcc
	v_cndmask_b32_e64 v177, v184, v177, s[38:39]
	v_lshl_add_u32 v176, v176, 2, s9
	v_lshl_add_u32 v177, v177, 2, s9
	ds_read_b32 v176, v176
	ds_read_b32 v177, v177
	v_add_u32_e32 v178, 27, v143
	v_add_u32_e32 v182, 27, v180
	v_add_u32_e32 v179, 59, v143
	v_add_u32_e32 v183, 59, v180
	v_cmp_gt_u32_e32 vcc, s4, v178
	v_cmp_gt_u32_e64 s[36:37], s99, v182
	v_cmp_gt_u32_e64 s[38:39], s4, v179
	v_cmp_gt_u32_e64 s[16:17], s99, v183
	s_and_b64 vcc, vcc, s[36:37]
	s_and_b64 s[38:39], s[38:39], s[16:17]
	v_cndmask_b32_e32 v178, v184, v178, vcc
	v_cndmask_b32_e64 v179, v184, v179, s[38:39]
	v_lshl_add_u32 v178, v178, 2, s9
	v_lshl_add_u32 v179, v179, 2, s9
	ds_read_b32 v178, v178
	ds_read_b32 v179, v179
	s_waitcnt lgkmcnt(6)
	v_add_f32_e32 v76, v76, v172
	v_add_f32_e32 v60, v60, v173
	v_exp_f32_e32 v181, v76
	v_exp_f32_e32 v76, v60
	v_mov_b32_e32 v60, v181
	s_waitcnt lgkmcnt(4)
	v_add_f32_e32 v77, v77, v174
	v_add_f32_e32 v61, v61, v175
	v_exp_f32_e32 v181, v77
	v_exp_f32_e32 v77, v61
	v_mov_b32_e32 v61, v181
	s_waitcnt lgkmcnt(2)
	v_add_f32_e32 v78, v78, v176
	v_add_f32_e32 v62, v62, v177
	v_exp_f32_e32 v181, v78
	v_exp_f32_e32 v78, v62
	v_mov_b32_e32 v62, v181
	s_waitcnt lgkmcnt(0)
	v_add_f32_e32 v79, v79, v178
	v_add_f32_e32 v63, v63, v179
	v_exp_f32_e32 v181, v79
	v_exp_f32_e32 v79, v63
	v_mov_b32_e32 v63, v181
	v_pk_add_f32 v[132:133], v[132:133], v[48:49]
	v_cvt_pk_bf16_f32 v48, v48, v49
	v_pk_add_f32 v[132:133], v[64:65], v[132:133]
	v_cvt_pk_bf16_f32 v64, v64, v65
	v_pk_add_f32 v[134:135], v[134:135], v[50:51]
	v_cvt_pk_bf16_f32 v65, v66, v67
	v_pk_add_f32 v[134:135], v[66:67], v[134:135]
	v_cvt_pk_bf16_f32 v49, v50, v51
	v_pk_add_f32 v[132:133], v[132:133], v[52:53]
	v_cvt_pk_bf16_f32 v66, v68, v69
	v_pk_add_f32 v[132:133], v[68:69], v[132:133]
	v_cvt_pk_bf16_f32 v50, v52, v53
	v_pk_add_f32 v[134:135], v[134:135], v[54:55]
	v_cvt_pk_bf16_f32 v67, v70, v71
	v_pk_add_f32 v[134:135], v[70:71], v[134:135]
	v_cvt_pk_bf16_f32 v51, v54, v55
	v_pk_add_f32 v[132:133], v[132:133], v[56:57]
	v_cvt_pk_bf16_f32 v56, v56, v57
	v_pk_add_f32 v[132:133], v[72:73], v[132:133]
	v_cvt_pk_bf16_f32 v72, v72, v73
	v_pk_add_f32 v[134:135], v[134:135], v[58:59]
	v_cvt_pk_bf16_f32 v73, v74, v75
	v_pk_add_f32 v[134:135], v[74:75], v[134:135]
	v_cvt_pk_bf16_f32 v57, v58, v59
	v_pk_add_f32 v[132:133], v[132:133], v[60:61]
	v_cvt_pk_bf16_f32 v74, v76, v77
	v_pk_add_f32 v[132:133], v[76:77], v[132:133]
	v_cvt_pk_bf16_f32 v58, v60, v61
	v_pk_add_f32 v[134:135], v[134:135], v[62:63]
	v_pk_add_f32 v[134:135], v[78:79], v[134:135]
	v_cvt_pk_bf16_f32 v75, v78, v79
	v_cvt_pk_bf16_f32 v59, v62, v63
	s_setprio 1
	v_mfma_f32_32x32x16_bf16 v[0:15], v[48:51], v[122:125], v[0:15]
	v_mfma_f32_32x32x16_bf16 v[16:31], v[48:51], v[126:129], v[16:31]
	v_mfma_f32_32x32x16_bf16 v[0:15], v[56:59], v[110:113], v[0:15]
	v_mfma_f32_32x32x16_bf16 v[16:31], v[56:59], v[118:121], v[16:31]
	v_mfma_f32_32x32x16_bf16 v[0:15], v[64:67], v[106:109], v[0:15]
	v_mfma_f32_32x32x16_bf16 v[16:31], v[64:67], v[114:117], v[16:31]
	v_mfma_f32_32x32x16_bf16 v[0:15], v[72:75], v[98:101], v[0:15]
	v_mfma_f32_32x32x16_bf16 v[16:31], v[72:75], v[102:105], v[16:31]
	s_setprio 0
	s_add_i32 s62, s62, 64
	v_add_u32_e32 v142, 0x4400, v142
	s_cmpk_eq_i32 s62, 0xc0
	v_add_u32_e32 v80, 0x4400, v80
	s_cbranch_scc0 .LBB0_787
	v_add_f32_e32 v32, v132, v133
	v_add_f32_e32 v33, v134, v135
	v_cmp_lt_i32_e32 vcc, v223, v217
	v_add_f32_e32 v32, v32, v33
	s_lshl_b32 s9, s58, 2
	v_cndmask_b32_e32 v33, v216, v223, vcc
	v_lshlrev_b32_e32 v33, 2, v33
	ds_bpermute_b32 v33, v33, v32
	s_add_i32 s9, s9, 0
	s_add_i32 s9, s9, 0x19800
	v_cmp_gt_u32_e32 vcc, 32, v139
	s_and_saveexec_b64 s[36:37], vcc
	s_cbranch_execz .LBB0_781
	s_waitcnt lgkmcnt(0)
	v_add_f32_e32 v32, v32, v33
	v_cmp_gt_f32_e32 vcc, s35, v32
	s_lshl_b64 s[16:17], s[42:43], 17
	v_lshl_add_u32 v34, v137, 2, s9
	v_cndmask_b32_e64 v33, 0, 32, vcc
	v_ldexp_f32 v33, v32, v33
	v_log_f32_e32 v33, v33
	s_add_u32 s16, s50, s16
	ds_write_b32 v34, v32
	v_mov_b32_e32 v32, 0x42000000
	s_addc_u32 s17, s51, s17
	s_lshl_b32 s18, s54, 2
	v_cndmask_b32_e32 v32, 0, v32, vcc
	s_add_u32 s16, s16, s18
	v_sub_f32_e32 v32, v33, v32
	s_addc_u32 s17, s17, 0
	v_add_f32_e32 v32, v138, v32
	v_mul_f32_e32 v34, 0x3f317218, v32
	v_lshl_add_u64 v[32:33], v[130:131], 4, s[16:17]
	global_store_dword v[32:33], v34, off
	s_branch .LBB0_781
